# adds: swa_prompt K/V tile staging with full-line loads issued together
# baseline (speedup 1.0000x reference)
; #define LAS __attribute__((address_space(3)))
; __device__ __forceinline__ void swa_prompt_unit(const Ctx& P, int li, int b, int qh, int n, LAS unsigned char* lds, const bf16_t* PROJ, bf16_t* H, int tid) {
;     ...
;     LAS unsigned char* Ks = lds; LAS unsigned char* VT = lds + 36864; LAS unsigned char* Pm = lds + 36864 + 33792;
;     const long R0 = (long)b * SEQ + (long)n * 128;
; #pragma unroll
;     for (int r = 0; r < 4; ++r) { const int idx = tid + 512 * r, jj = idx & 255, seg = idx >> 8;
;         const bool valid = (n > 0) || (jj >= 128);
;         u32x4 kv = {0u, 0u, 0u, 0u}, vv = {0u, 0u, 0u, 0u};
;         if (valid) { const bf16_t* rp = PROJ + (size_t)(R0 - 128 + jj) * EIN + kvh * 64 + seg * 8; kv = *(const u32x4*)(rp + 5120); vv = *(const u32x4*)(rp + 5248); }
;         *(LAS u32x4*)(Ks + jj * 144 + seg * 16) = kv;
; #pragma unroll
;         for (int i = 0; i < 4; ++i) {
;             *(LAS bf16_t*)(VT + (seg * 8 + 2 * i) * 528 + jj * 2) = (bf16_t)(vv[i] & 0xffffu);
;             *(LAS bf16_t*)(VT + (seg * 8 + 2 * i + 1) * 528 + jj * 2) = (bf16_t)(vv[i] >> 16); } }
;     __syncthreads();
.LBB0_445:
	v_mov_b32_e32 v47, v179
	s_cmpk_gt_i32 s38, 0x3ff
	s_cbranch_scc1 .LBB0_469
	s_ashr_i32 s0, s38, 9
	s_and_b32 s4, s38, 31
	s_ashr_i32 s1, s0, 31
	s_lshl_b64 s[0:1], s[0:1], 12
	s_lshl_b32 s5, s4, 7
	s_or_b32 s0, s0, s5
	v_and_b32_e32 v128, 0xff, v47
	s_movk_i32 s20, 0xff80
	v_lshl_add_u64 v[0:1], v[128:129], 0, s[0:1]
	s_mov_b32 s21, -1
	v_lshl_add_u64 v[0:1], v[0:1], 0, s[20:21]
	v_mov_b64_e32 v[2:3], s[14:15]
	s_cmp_lg_u32 s4, 0
	v_mad_u64_u32 v[2:3], s[20:21], v0, s35, v[2:3]
	s_cselect_b64 s[4:5], -1, 0
	s_movk_i32 s18, 0x7f
	s_lshr_b32 s20, s38, 1
	v_cmp_lt_u32_e32 vcc, s18, v128
	v_mad_i32_i24 v3, v1, s35, v3
	s_and_b32 s24, s20, 0x80
	s_waitcnt vmcnt(10)
	v_mov_b32_e32 v6, 0
	s_or_b64 s[18:19], s[4:5], vcc
	s_waitcnt vmcnt(9)
	v_lshl_add_u64 v[10:11], v[2:3], 0, s[24:25]
	v_ashrrev_i32_e32 v1, 8, v47
	v_mov_b32_e32 v0, 0
	v_mov_b32_e32 v2, 0
	v_mov_b32_e32 v3, 0
	v_mov_b32_e32 v4, 0
	v_mov_b32_e32 v5, 0
	v_mov_b32_e32 v7, v6
	v_mov_b32_e32 v8, v6
	v_mov_b32_e32 v9, v6
	v_lshrrev_b32_e32 v200, 3, v47
	v_and_b32_e32 v201, 7, v47
	v_sub_u32_e32 v204, v200, v128
	v_mov_b32_e32 v205, 0
	v_mad_i64_i32 v[202:203], s[20:21], v204, s35, v[10:11]
	v_lshlrev_b32_e32 v204, 4, v201
	v_mul_u32_u24_e32 v244, 0x90, v200
	v_lshl_add_u64 v[202:203], v[202:203], 0, v[204:205]
	s_mov_b64 s[20:21], 0x2000
	v_mul_u32_u24_e32 v245, 0x1080, v201
	v_lshl_add_u64 v[202:203], v[202:203], 0, s[20:21]
	s_mov_b32 s20, 0xa8000
	s_mov_b32 s21, 0
	v_lshl_add_u32 v244, v201, 4, v244
	v_lshl_add_u32 v245, v200, 1, v245
	s_and_b64 vcc, exec, s[4:5]
	s_cbranch_vccz .Lswp_first_tile
	global_load_dwordx4 v[212:215], v[202:203], off offset:2048
	global_load_dwordx4 v[216:219], v[202:203], off offset:2304
	v_lshl_add_u64 v[202:203], v[202:203], 0, s[20:21]
	global_load_dwordx4 v[220:223], v[202:203], off offset:2048
	global_load_dwordx4 v[224:227], v[202:203], off offset:2304
	v_lshl_add_u64 v[202:203], v[202:203], 0, s[20:21]
	s_branch .Lswp_second_half
.Lswp_first_tile:
	v_mov_b32_e32 v212, 0
	v_mov_b32_e32 v213, 0
	v_mov_b32_e32 v214, 0
	v_mov_b32_e32 v215, 0
	v_mov_b32_e32 v216, 0
	v_mov_b32_e32 v217, 0
	v_mov_b32_e32 v218, 0
	v_mov_b32_e32 v219, 0
	v_mov_b32_e32 v220, 0
	v_mov_b32_e32 v221, 0
	v_mov_b32_e32 v222, 0
	v_mov_b32_e32 v223, 0
	v_mov_b32_e32 v224, 0
	v_mov_b32_e32 v225, 0
	v_mov_b32_e32 v226, 0
	v_mov_b32_e32 v227, 0
	v_lshl_add_u64 v[202:203], v[202:203], 0, s[20:21]
	v_lshl_add_u64 v[202:203], v[202:203], 0, s[20:21]
.Lswp_second_half:
	global_load_dwordx4 v[228:231], v[202:203], off offset:2048
	global_load_dwordx4 v[232:235], v[202:203], off offset:2304
	v_lshl_add_u64 v[202:203], v[202:203], 0, s[20:21]
	global_load_dwordx4 v[236:239], v[202:203], off offset:2048
	global_load_dwordx4 v[240:243], v[202:203], off offset:2304
	s_waitcnt vmcnt(0)
	ds_write_b128 v244, v[212:215]
	ds_write_b16 v245, v216 offset:36864
	ds_write_b16_d16_hi v245, v216 offset:37392
	ds_write_b16 v245, v217 offset:37920
	ds_write_b16_d16_hi v245, v217 offset:38448
	ds_write_b16 v245, v218 offset:38976
	ds_write_b16_d16_hi v245, v218 offset:39504
	ds_write_b16 v245, v219 offset:40032
	ds_write_b16_d16_hi v245, v219 offset:40560
	ds_write_b128 v244, v[220:223] offset:9216
	ds_write_b16 v245, v224 offset:36992
	ds_write_b16_d16_hi v245, v224 offset:37520
	ds_write_b16 v245, v225 offset:38048
	ds_write_b16_d16_hi v245, v225 offset:38576
	ds_write_b16 v245, v226 offset:39104
	ds_write_b16_d16_hi v245, v226 offset:39632
	ds_write_b16 v245, v227 offset:40160
	ds_write_b16_d16_hi v245, v227 offset:40688
	ds_write_b128 v244, v[228:231] offset:18432
	ds_write_b16 v245, v232 offset:37120
	ds_write_b16_d16_hi v245, v232 offset:37648
	ds_write_b16 v245, v233 offset:38176
	ds_write_b16_d16_hi v245, v233 offset:38704
	ds_write_b16 v245, v234 offset:39232
	ds_write_b16_d16_hi v245, v234 offset:39760
	ds_write_b16 v245, v235 offset:40288
	ds_write_b16_d16_hi v245, v235 offset:40816
	ds_write_b128 v244, v[236:239] offset:27648
	ds_write_b16 v245, v240 offset:37248
	ds_write_b16_d16_hi v245, v240 offset:37776
	ds_write_b16 v245, v241 offset:38304
	ds_write_b16_d16_hi v245, v241 offset:38832
	ds_write_b16 v245, v242 offset:39360
	ds_write_b16_d16_hi v245, v242 offset:39888
	ds_write_b16 v245, v243 offset:40416
	ds_write_b16_d16_hi v245, v243 offset:40944
	v_ashrrev_i32_e32 v0, 2, v47
	v_bfi_b32 v50, -16, v0, v47
	v_ashrrev_i32_e32 v51, 31, v50
	v_lshl_add_u64 v[44:45], s[0:1], 0, v[50:51]
	v_mov_b64_e32 v[0:1], s[14:15]
	v_mad_u64_u32 v[0:1], s[0:1], v44, s35, v[0:1]
	s_lshr_b32 s18, s38, 5
	v_mov_b32_e32 v2, v1
	s_and_b32 s18, s18, 15
	v_mad_u64_u32 v[2:3], s[0:1], v45, s35, v[2:3]
	v_bfe_u32 v62, v47, 4, 2
	v_mov_b32_e32 v1, v2
	s_lshl_b32 s24, s18, 7
	v_lshl_add_u64 v[0:1], v[0:1], 0, s[24:25]
	v_lshlrev_b32_e32 v48, 4, v62
	v_mov_b32_e32 v49, v129
	v_lshl_add_u64 v[0:1], v[0:1], 0, v[48:49]
	s_mov_b64 s[0:1], 0x2000
	v_lshl_add_u64 v[2:3], v[0:1], 0, s[0:1]
	v_add_co_u32_e32 v0, vcc, s62, v0
	s_waitcnt lgkmcnt(0)
	s_nop 0
	v_addc_co_u32_e32 v1, vcc, 0, v1, vcc
	s_barrier
; #define LAS __attribute__((address_space(3)))
; __device__ __forceinline__ f32x4 mfma16(bf16x8 a, bf16x8 b, f32x4 c) { return __builtin_amdgcn_mfma_f32_16x16x32_bf16(a, b, c, 0, 0, 0); }
; __device__ __forceinline__ void swa_prompt_unit(const Ctx& P, int li, int b, int qh, int n, LAS unsigned char* lds, const bf16_t* PROJ, bf16_t* H, int tid) {
;     ...
;     const int i = 16 * wave + fr;
;     const size_t qrow = (size_t)R0 + i;
;     bf16x8 qf[2];
; #pragma unroll
;     for (int kk = 0; kk < 2; ++kk) qf[kk] = *(const bf16x8*)(PROJ + qrow * EIN + 4096 + qh * 64 + 32 * kk + 8 * fq);
;     const int cb0 = 2 * (wave >> 1);
;     f32x4 sc[10];
; #pragma unroll
;     for (int cbi = 0; cbi < 10; ++cbi) { f32x4 acc = {0.f, 0.f, 0.f, 0.f};
; #pragma unroll
;         for (int kk = 0; kk < 2; ++kk) { const bf16x8 kf = *(const LAS bf16x8*)(Ks + (16 * (cb0 + cbi) + fr) * 144 + (32 * kk + 8 * fq) * 2); acc = mfma16(kf, qf[kk], acc); }
;         sc[cbi] = acc; }
;     const float slope = exp2f(-0.5f * (float)(qh + 1)), sink = P.in[I_SINK][li * 16 + qh];
;     float mx = -INFINITY;
; #pragma unroll
;     for (int cbi = 0; cbi < 10; ++cbi)
; #pragma unroll
;         for (int t = 0; t < 4; ++t) { const int jj = 16 * (cb0 + cbi) + 4 * fq + t, dist = i + 128 - jj;
;             const bool valid = dist >= 0 && dist <= 128 && (n > 0 || jj >= 128);
;             const float s = valid ? sc[cbi][t] * 0.125f - slope * (float)dist : -INFINITY; sc[cbi][t] = s; mx = fmaxf(mx, s); }
	global_load_dwordx4 v[40:43], v[0:1], off
	s_nop 0
	global_load_dwordx4 v[0:3], v[2:3], off offset:64
	v_ashrrev_i32_e32 v49, 7, v47
	v_and_b32_e32 v52, 15, v47
	v_lshlrev_b32_e32 v78, 5, v49
	v_add_u32_e32 v46, 0, v48
	v_or_b32_e32 v4, v78, v52
	s_movk_i32 s19, 0x90
	v_mad_u64_u32 v[8:9], s[0:1], v4, s19, v[46:47]
	ds_read_b128 v[4:7], v8
	ds_read_b128 v[8:11], v8 offset:64
	v_lshlrev_b32_e32 v71, 1, v49
	v_or_b32_e32 v51, 1, v71
	v_lshlrev_b32_e32 v70, 4, v51
	v_add_u32_e32 v53, 2, v71
	v_lshlrev_b32_e32 v69, 4, v53
	v_add_u32_e32 v54, 3, v71
	v_lshlrev_b32_e32 v68, 4, v54
	v_add_u32_e32 v55, 4, v71
	v_lshlrev_b32_e32 v67, 4, v55
	v_add_u32_e32 v56, 5, v71
	v_lshlrev_b32_e32 v66, 4, v56
	v_add_u32_e32 v57, 6, v71
	v_lshlrev_b32_e32 v65, 4, v57
	v_add_u32_e32 v58, 7, v71
	v_lshlrev_b32_e32 v64, 4, v58
	v_add_u32_e32 v59, 8, v71
	v_lshlrev_b32_e32 v63, 4, v59
	v_lshlrev_b32_e32 v128, 3, v62
	v_lshlrev_b32_e32 v62, 2, v62
	s_movk_i32 s20, 0x7e
	s_waitcnt vmcnt(1) lgkmcnt(1)
	v_mfma_f32_16x16x32_bf16 v[4:7], v[4:7], v[40:43], 0
	s_waitcnt vmcnt(0) lgkmcnt(0)
	v_mfma_f32_16x16x32_bf16 v[36:39], v[8:11], v[0:3], v[4:7]
	s_nop 5
	v_or_b32_e32 v4, v70, v52
	v_mad_u64_u32 v[8:9], s[0:1], v4, s19, v[46:47]
	ds_read_b128 v[4:7], v8
	ds_read_b128 v[8:11], v8 offset:64
	s_waitcnt lgkmcnt(1)
	v_mfma_f32_16x16x32_bf16 v[4:7], v[4:7], v[40:43], 0
	s_waitcnt lgkmcnt(0)
	v_mfma_f32_16x16x32_bf16 v[32:35], v[8:11], v[0:3], v[4:7]
	s_nop 5
	v_or_b32_e32 v4, v69, v52
	v_mad_u64_u32 v[8:9], s[0:1], v4, s19, v[46:47]
	ds_read_b128 v[4:7], v8
	ds_read_b128 v[8:11], v8 offset:64
	s_waitcnt lgkmcnt(1)
	v_mfma_f32_16x16x32_bf16 v[4:7], v[4:7], v[40:43], 0
	v_or_b32_e32 v69, v69, v62
	s_waitcnt lgkmcnt(0)
	v_mfma_f32_16x16x32_bf16 v[28:31], v[8:11], v[0:3], v[4:7]
	s_nop 4
	v_or_b32_e32 v4, v68, v52
	v_mad_u64_u32 v[8:9], s[0:1], v4, s19, v[46:47]
	ds_read_b128 v[4:7], v8
	ds_read_b128 v[8:11], v8 offset:64
	s_waitcnt lgkmcnt(1)
	v_mfma_f32_16x16x32_bf16 v[4:7], v[4:7], v[40:43], 0
	s_waitcnt lgkmcnt(0)
	v_mfma_f32_16x16x32_bf16 v[24:27], v[8:11], v[0:3], v[4:7]
	s_nop 5
	v_or_b32_e32 v4, v67, v52
	v_mad_u64_u32 v[8:9], s[0:1], v4, s19, v[46:47]
	ds_read_b128 v[4:7], v8
	ds_read_b128 v[8:11], v8 offset:64
	s_waitcnt lgkmcnt(1)
	v_mfma_f32_16x16x32_bf16 v[4:7], v[4:7], v[40:43], 0
	v_or_b32_e32 v67, v67, v62
	s_waitcnt lgkmcnt(0)
	v_mfma_f32_16x16x32_bf16 v[20:23], v[8:11], v[0:3], v[4:7]
	s_nop 4
	v_or_b32_e32 v4, v66, v52
	v_mad_u64_u32 v[8:9], s[0:1], v4, s19, v[46:47]
	ds_read_b128 v[4:7], v8
	ds_read_b128 v[8:11], v8 offset:64
	s_waitcnt lgkmcnt(1)
	v_mfma_f32_16x16x32_bf16 v[4:7], v[4:7], v[40:43], 0
	s_waitcnt lgkmcnt(0)
	v_mfma_f32_16x16x32_bf16 v[16:19], v[8:11], v[0:3], v[4:7]
	s_nop 5
	v_or_b32_e32 v4, v65, v52
	v_mad_u64_u32 v[8:9], s[0:1], v4, s19, v[46:47]
	ds_read_b128 v[4:7], v8
	ds_read_b128 v[8:11], v8 offset:64
	s_waitcnt lgkmcnt(1)
	v_mfma_f32_16x16x32_bf16 v[4:7], v[4:7], v[40:43], 0
	v_or_b32_e32 v65, v65, v62
	s_waitcnt lgkmcnt(0)
	v_mfma_f32_16x16x32_bf16 v[12:15], v[8:11], v[0:3], v[4:7]
	s_nop 4
	v_or_b32_e32 v4, v64, v52
	v_mad_u64_u32 v[8:9], s[0:1], v4, s19, v[46:47]
	ds_read_b128 v[4:7], v8
	ds_read_b128 v[8:11], v8 offset:64
	s_waitcnt lgkmcnt(1)
	v_mfma_f32_16x16x32_bf16 v[4:7], v[4:7], v[40:43], 0
	s_waitcnt lgkmcnt(0)
	v_mfma_f32_16x16x32_bf16 v[8:11], v[8:11], v[0:3], v[4:7]
	s_nop 5
	v_or_b32_e32 v4, v63, v52
	v_mad_u64_u32 v[60:61], s[0:1], v4, s19, v[46:47]
	ds_read_b128 v[4:7], v60
	ds_read_b128 v[72:75], v60 offset:64
	s_waitcnt lgkmcnt(1)
	v_mfma_f32_16x16x32_bf16 v[4:7], v[4:7], v[40:43], 0
	v_add_u32_e32 v60, 9, v71
	v_lshlrev_b32_e32 v61, 4, v60
	v_or_b32_e32 v71, v61, v52
	v_mad_u64_u32 v[76:77], s[0:1], v71, s19, v[46:47]
	s_waitcnt lgkmcnt(0)
	v_mfma_f32_16x16x32_bf16 v[4:7], v[72:75], v[0:3], v[4:7]
	ds_read_b128 v[72:75], v76
	s_add_i32 s0, s18, 1
	v_or_b32_e32 v71, v62, v78
	s_waitcnt lgkmcnt(0)
	v_mfma_f32_16x16x32_bf16 v[40:43], v[72:75], v[40:43], 0
	ds_read_b128 v[72:75], v76 offset:64
	s_movk_i32 s19, 0x81
	v_or_b32_e32 v63, v63, v62
	s_waitcnt lgkmcnt(0)
	v_mfma_f32_16x16x32_bf16 v[0:3], v[72:75], v[0:3], v[40:43]
	s_nop 2
	v_cvt_f32_ubyte0_e32 v40, s0
	v_mul_f32_e32 v41, -0.5, v40
	v_cmp_gt_f32_e32 vcc, s34, v41
	s_and_b64 s[0:1], vcc, exec
	s_cselect_b32 s0, 0xffffffc0, 0
	v_cndmask_b32_e32 v41, 0, v168, vcc
	v_fmac_f32_e32 v41, -0.5, v40
	v_exp_f32_e32 v40, v41
	v_add_u32_e32 v43, 0x80, v50
	v_or_b32_e32 v61, v61, v62
	v_ldexp_f32 v41, v40, s0
	v_sub_u32_e32 v40, v43, v71
	s_or_b32 s0, s18, s13
	v_cvt_f32_u32_e32 v133, v40
	s_ashr_i32 s1, s0, 31
	s_lshl_b64 s[0:1], s[0:1], 2
	s_add_u32 s0, s76, s0
	v_cmp_gt_u32_e32 vcc, s19, v40
	v_mov_b32_e32 v40, v36
	s_addc_u32 s1, s77, s1
	s_movk_i32 s18, 0x7f
	v_pk_mul_f32 v[72:73], v[40:41], v[132:133]
	v_xad_u32 v40, v71, -1, v43
	global_load_dword v42, v129, s[0:1]
	v_cmp_lt_i32_e64 s[0:1], s18, v71
	v_cvt_f32_u32_e32 v133, v40
	s_or_b64 s[0:1], s[4:5], s[0:1]
	s_and_b64 vcc, vcc, s[0:1]
	v_sub_f32_e32 v36, v72, v73
	v_cndmask_b32_e32 v36, v178, v36, vcc
	v_cmp_gt_u32_e32 vcc, s19, v40
	v_mov_b32_e32 v40, v37
	v_pk_mul_f32 v[72:73], v[40:41], v[132:133]
	v_or_b32_e32 v40, 2, v71
	v_cmp_lt_i32_e64 s[0:1], s20, v71
	v_sub_f32_e32 v37, v72, v73
	v_sub_u32_e32 v72, v43, v40
	s_or_b64 s[0:1], s[4:5], s[0:1]
	v_cvt_f32_u32_e32 v133, v72
	s_and_b64 vcc, vcc, s[0:1]
	v_cndmask_b32_e32 v37, v178, v37, vcc
	s_mov_b32 s0, 0xff800000
	v_max3_f32 v74, v36, s0, v37
	v_cmp_lt_i32_e64 s[0:1], s18, v40
	v_mov_b32_e32 v40, v38
	v_cmp_gt_u32_e32 vcc, s19, v72
	v_pk_mul_f32 v[72:73], v[40:41], v[132:133]
	v_or_b32_e32 v40, 3, v71
	v_sub_u32_e32 v71, v43, v40
	v_cvt_f32_u32_e32 v133, v71
; __device__ __forceinline__ void swa_prompt_unit(const Ctx& P, int li, int b, int qh, int n, LAS unsigned char* lds, const bf16_t* PROJ, bf16_t* H, int tid) {
;     ...
;     for (int cbi = 0; cbi < 10; ++cbi)
; #pragma unroll
;         for (int t = 0; t < 4; ++t) { const int jj = 16 * (cb0 + cbi) + 4 * fq + t, dist = i + 128 - jj;
;             const bool valid = dist >= 0 && dist <= 128 && (n > 0 || jj >= 128);
;             const float s = valid ? sc[cbi][t] * 0.125f - slope * (float)dist : -INFINITY; sc[cbi][t] = s; mx = fmaxf(mx, s); }
	s_or_b64 s[0:1], s[4:5], s[0:1]
	s_and_b64 vcc, vcc, s[0:1]
	v_cmp_lt_i32_e64 s[0:1], s18, v40
	v_mov_b32_e32 v40, v39
	v_sub_f32_e32 v38, v72, v73
	v_pk_mul_f32 v[72:73], v[40:41], v[132:133]
	v_cndmask_b32_e32 v38, v178, v38, vcc
	v_sub_f32_e32 v39, v72, v73
	v_or_b32_e32 v73, v70, v62
	v_sub_u32_e32 v40, v43, v73
	v_cvt_f32_u32_e32 v133, v40
	v_cmp_gt_u32_e32 vcc, s19, v71
	s_or_b64 s[0:1], s[4:5], s[0:1]
	s_and_b64 vcc, vcc, s[0:1]
	v_cndmask_b32_e32 v39, v178, v39, vcc
	v_cmp_gt_u32_e32 vcc, s19, v40
	v_mov_b32_e32 v40, v32
	v_pk_mul_f32 v[70:71], v[40:41], v[132:133]
	v_xad_u32 v40, v73, -1, v43
	v_cmp_lt_i32_e64 s[0:1], s18, v73
	v_cvt_f32_u32_e32 v133, v40
	s_or_b64 s[0:1], s[4:5], s[0:1]
	s_and_b64 vcc, vcc, s[0:1]
	v_sub_f32_e32 v32, v70, v71
	v_cndmask_b32_e32 v32, v178, v32, vcc
	v_cmp_gt_u32_e32 vcc, s19, v40
	v_mov_b32_e32 v40, v33
	v_pk_mul_f32 v[70:71], v[40:41], v[132:133]
	v_or_b32_e32 v40, 2, v73
	v_sub_f32_e32 v33, v70, v71
	v_sub_u32_e32 v70, v43, v40
	v_cvt_f32_u32_e32 v133, v70
	v_cmp_lt_i32_e64 s[0:1], s20, v73
	s_or_b64 s[0:1], s[4:5], s[0:1]
	s_and_b64 vcc, vcc, s[0:1]
	v_cmp_lt_i32_e64 s[0:1], s18, v40
	v_mov_b32_e32 v40, v34
	v_cndmask_b32_e32 v33, v178, v33, vcc
	v_cmp_gt_u32_e32 vcc, s19, v70
	v_pk_mul_f32 v[70:71], v[40:41], v[132:133]
	v_or_b32_e32 v40, 3, v73
	v_sub_f32_e32 v34, v70, v71
	v_sub_u32_e32 v70, v43, v40
	v_cvt_f32_u32_e32 v133, v70
	s_or_b64 s[0:1], s[4:5], s[0:1]
	s_and_b64 vcc, vcc, s[0:1]
	v_cmp_lt_i32_e64 s[0:1], s18, v40
	v_mov_b32_e32 v40, v35
	v_cndmask_b32_e32 v34, v178, v34, vcc
	v_cmp_gt_u32_e32 vcc, s19, v70
	v_pk_mul_f32 v[70:71], v[40:41], v[132:133]
	v_sub_u32_e32 v40, v43, v69
	v_cvt_f32_u32_e32 v133, v40
	s_or_b64 s[0:1], s[4:5], s[0:1]
	s_and_b64 vcc, vcc, s[0:1]
	v_sub_f32_e32 v35, v70, v71
	v_cndmask_b32_e32 v35, v178, v35, vcc
	v_cmp_gt_u32_e32 vcc, s19, v40
	v_mov_b32_e32 v40, v28
	v_pk_mul_f32 v[70:71], v[40:41], v[132:133]
	v_xad_u32 v40, v69, -1, v43
	v_cmp_lt_i32_e64 s[0:1], s18, v69
	v_cvt_f32_u32_e32 v133, v40
	s_or_b64 s[0:1], s[4:5], s[0:1]
	s_and_b64 vcc, vcc, s[0:1]
	v_sub_f32_e32 v28, v70, v71
	v_cndmask_b32_e32 v28, v178, v28, vcc
	v_cmp_gt_u32_e32 vcc, s19, v40
	v_mov_b32_e32 v40, v29
	v_pk_mul_f32 v[70:71], v[40:41], v[132:133]
	v_or_b32_e32 v40, 2, v69
	v_sub_f32_e32 v29, v70, v71
	v_sub_u32_e32 v70, v43, v40
	v_cvt_f32_u32_e32 v133, v70
	v_cmp_lt_i32_e64 s[0:1], s20, v69
	s_or_b64 s[0:1], s[4:5], s[0:1]
	s_and_b64 vcc, vcc, s[0:1]
	v_cmp_lt_i32_e64 s[0:1], s18, v40
	v_mov_b32_e32 v40, v30
	v_cndmask_b32_e32 v29, v178, v29, vcc
	v_cmp_gt_u32_e32 vcc, s19, v70
	v_pk_mul_f32 v[70:71], v[40:41], v[132:133]
	v_or_b32_e32 v40, 3, v69
	v_sub_u32_e32 v69, v43, v40
	v_cvt_f32_u32_e32 v133, v69
	s_or_b64 s[0:1], s[4:5], s[0:1]
	s_and_b64 vcc, vcc, s[0:1]
	v_cmp_lt_i32_e64 s[0:1], s18, v40
	v_mov_b32_e32 v40, v31
	v_sub_f32_e32 v30, v70, v71
	v_pk_mul_f32 v[70:71], v[40:41], v[132:133]
	v_cndmask_b32_e32 v30, v178, v30, vcc
	v_sub_f32_e32 v31, v70, v71
	v_or_b32_e32 v71, v68, v62
	v_sub_u32_e32 v40, v43, v71
	v_cvt_f32_u32_e32 v133, v40
	v_cmp_gt_u32_e32 vcc, s19, v69
	s_or_b64 s[0:1], s[4:5], s[0:1]
	s_and_b64 vcc, vcc, s[0:1]
	v_cndmask_b32_e32 v31, v178, v31, vcc
	v_cmp_gt_u32_e32 vcc, s19, v40
	v_mov_b32_e32 v40, v24
	v_pk_mul_f32 v[68:69], v[40:41], v[132:133]
	v_xad_u32 v40, v71, -1, v43
	v_cmp_lt_i32_e64 s[0:1], s18, v71
	v_cvt_f32_u32_e32 v133, v40
	s_or_b64 s[0:1], s[4:5], s[0:1]
	s_and_b64 vcc, vcc, s[0:1]
	v_sub_f32_e32 v24, v68, v69
	v_cndmask_b32_e32 v24, v178, v24, vcc
	v_cmp_gt_u32_e32 vcc, s19, v40
	v_mov_b32_e32 v40, v25
	v_pk_mul_f32 v[68:69], v[40:41], v[132:133]
	v_or_b32_e32 v40, 2, v71
	v_sub_f32_e32 v25, v68, v69
	v_sub_u32_e32 v68, v43, v40
	v_cvt_f32_u32_e32 v133, v68
	v_cmp_lt_i32_e64 s[0:1], s20, v71
	s_or_b64 s[0:1], s[4:5], s[0:1]
	s_and_b64 vcc, vcc, s[0:1]
	v_cmp_lt_i32_e64 s[0:1], s18, v40
	v_mov_b32_e32 v40, v26
	v_cndmask_b32_e32 v25, v178, v25, vcc
	v_cmp_gt_u32_e32 vcc, s19, v68
	v_pk_mul_f32 v[68:69], v[40:41], v[132:133]
	v_or_b32_e32 v40, 3, v71
	v_sub_f32_e32 v26, v68, v69
	v_sub_u32_e32 v68, v43, v40
	v_cvt_f32_u32_e32 v133, v68
	s_or_b64 s[0:1], s[4:5], s[0:1]
	s_and_b64 vcc, vcc, s[0:1]
	v_cmp_lt_i32_e64 s[0:1], s18, v40
	v_mov_b32_e32 v40, v27
	v_cndmask_b32_e32 v26, v178, v26, vcc
	v_cmp_gt_u32_e32 vcc, s19, v68
	v_pk_mul_f32 v[68:69], v[40:41], v[132:133]
	v_sub_u32_e32 v40, v43, v67
	v_cvt_f32_u32_e32 v133, v40
	s_or_b64 s[0:1], s[4:5], s[0:1]
	s_and_b64 vcc, vcc, s[0:1]
	v_sub_f32_e32 v27, v68, v69
	v_cndmask_b32_e32 v27, v178, v27, vcc
	v_cmp_gt_u32_e32 vcc, s19, v40
	v_mov_b32_e32 v40, v20
	v_pk_mul_f32 v[68:69], v[40:41], v[132:133]
	v_xad_u32 v40, v67, -1, v43
	v_cmp_lt_i32_e64 s[0:1], s18, v67
	v_cvt_f32_u32_e32 v133, v40
	s_or_b64 s[0:1], s[4:5], s[0:1]
	s_and_b64 vcc, vcc, s[0:1]
	v_sub_f32_e32 v20, v68, v69
	v_cndmask_b32_e32 v20, v178, v20, vcc
	v_cmp_gt_u32_e32 vcc, s19, v40
	v_mov_b32_e32 v40, v21
	v_pk_mul_f32 v[68:69], v[40:41], v[132:133]
	v_or_b32_e32 v40, 2, v67
	v_sub_f32_e32 v21, v68, v69
	v_sub_u32_e32 v68, v43, v40
	v_cvt_f32_u32_e32 v133, v68
	v_cmp_lt_i32_e64 s[0:1], s20, v67
	s_or_b64 s[0:1], s[4:5], s[0:1]
	s_and_b64 vcc, vcc, s[0:1]
	v_cmp_lt_i32_e64 s[0:1], s18, v40
	v_mov_b32_e32 v40, v22
	v_cndmask_b32_e32 v21, v178, v21, vcc
	v_cmp_gt_u32_e32 vcc, s19, v68
	v_pk_mul_f32 v[68:69], v[40:41], v[132:133]
	v_or_b32_e32 v40, 3, v67
	v_sub_u32_e32 v67, v43, v40
	v_cvt_f32_u32_e32 v133, v67
	s_or_b64 s[0:1], s[4:5], s[0:1]
	s_and_b64 vcc, vcc, s[0:1]
	v_cmp_lt_i32_e64 s[0:1], s18, v40
	v_mov_b32_e32 v40, v23
	v_sub_f32_e32 v22, v68, v69
	v_pk_mul_f32 v[68:69], v[40:41], v[132:133]
; __device__ __forceinline__ void swa_prompt_unit(const Ctx& P, int li, int b, int qh, int n, LAS unsigned char* lds, const bf16_t* PROJ, bf16_t* H, int tid) {
;     ...
;     for (int cbi = 0; cbi < 10; ++cbi)
; #pragma unroll
;         for (int t = 0; t < 4; ++t) { const int jj = 16 * (cb0 + cbi) + 4 * fq + t, dist = i + 128 - jj;
;             const bool valid = dist >= 0 && dist <= 128 && (n > 0 || jj >= 128);
;             const float s = valid ? sc[cbi][t] * 0.125f - slope * (float)dist : -INFINITY; sc[cbi][t] = s; mx = fmaxf(mx, s); }
	v_cndmask_b32_e32 v22, v178, v22, vcc
	v_sub_f32_e32 v23, v68, v69
	v_or_b32_e32 v69, v66, v62
	v_sub_u32_e32 v40, v43, v69
	v_cvt_f32_u32_e32 v133, v40
	v_cmp_gt_u32_e32 vcc, s19, v67
	s_or_b64 s[0:1], s[4:5], s[0:1]
	s_and_b64 vcc, vcc, s[0:1]
	v_cndmask_b32_e32 v23, v178, v23, vcc
	v_cmp_gt_u32_e32 vcc, s19, v40
	v_mov_b32_e32 v40, v16
	v_pk_mul_f32 v[66:67], v[40:41], v[132:133]
	v_xad_u32 v40, v69, -1, v43
	v_cmp_lt_i32_e64 s[0:1], s18, v69
	v_cvt_f32_u32_e32 v133, v40
	s_or_b64 s[0:1], s[4:5], s[0:1]
	s_and_b64 vcc, vcc, s[0:1]
	v_sub_f32_e32 v16, v66, v67
	v_cndmask_b32_e32 v16, v178, v16, vcc
	v_cmp_gt_u32_e32 vcc, s19, v40
	v_mov_b32_e32 v40, v17
	v_pk_mul_f32 v[66:67], v[40:41], v[132:133]
	v_or_b32_e32 v40, 2, v69
	v_sub_f32_e32 v17, v66, v67
	v_sub_u32_e32 v66, v43, v40
	v_cvt_f32_u32_e32 v133, v66
	v_cmp_lt_i32_e64 s[0:1], s20, v69
	s_or_b64 s[0:1], s[4:5], s[0:1]
	s_and_b64 vcc, vcc, s[0:1]
	v_cmp_lt_i32_e64 s[0:1], s18, v40
	v_mov_b32_e32 v40, v18
	v_cndmask_b32_e32 v17, v178, v17, vcc
	v_cmp_gt_u32_e32 vcc, s19, v66
	v_pk_mul_f32 v[66:67], v[40:41], v[132:133]
	v_or_b32_e32 v40, 3, v69
	v_sub_f32_e32 v18, v66, v67
	v_sub_u32_e32 v66, v43, v40
	v_cvt_f32_u32_e32 v133, v66
	s_or_b64 s[0:1], s[4:5], s[0:1]
	s_and_b64 vcc, vcc, s[0:1]
	v_cmp_lt_i32_e64 s[0:1], s18, v40
	v_mov_b32_e32 v40, v19
	v_cndmask_b32_e32 v18, v178, v18, vcc
	v_cmp_gt_u32_e32 vcc, s19, v66
	v_pk_mul_f32 v[66:67], v[40:41], v[132:133]
	v_sub_u32_e32 v40, v43, v65
	v_cvt_f32_u32_e32 v133, v40
	s_or_b64 s[0:1], s[4:5], s[0:1]
	s_and_b64 vcc, vcc, s[0:1]
	v_sub_f32_e32 v19, v66, v67
	v_cndmask_b32_e32 v19, v178, v19, vcc
	v_cmp_gt_u32_e32 vcc, s19, v40
	v_mov_b32_e32 v40, v12
	v_pk_mul_f32 v[66:67], v[40:41], v[132:133]
	v_xad_u32 v40, v65, -1, v43
	v_cmp_lt_i32_e64 s[0:1], s18, v65
	v_cvt_f32_u32_e32 v133, v40
	s_or_b64 s[0:1], s[4:5], s[0:1]
	s_and_b64 vcc, vcc, s[0:1]
	v_sub_f32_e32 v12, v66, v67
	v_cndmask_b32_e32 v12, v178, v12, vcc
	v_cmp_gt_u32_e32 vcc, s19, v40
	v_mov_b32_e32 v40, v13
	v_pk_mul_f32 v[66:67], v[40:41], v[132:133]
	v_or_b32_e32 v40, 2, v65
	v_sub_f32_e32 v13, v66, v67
	v_sub_u32_e32 v66, v43, v40
	v_cvt_f32_u32_e32 v133, v66
	v_cmp_lt_i32_e64 s[0:1], s20, v65
	s_or_b64 s[0:1], s[4:5], s[0:1]
	s_and_b64 vcc, vcc, s[0:1]
	v_cmp_lt_i32_e64 s[0:1], s18, v40
	v_mov_b32_e32 v40, v14
	v_cndmask_b32_e32 v13, v178, v13, vcc
	v_cmp_gt_u32_e32 vcc, s19, v66
	v_pk_mul_f32 v[66:67], v[40:41], v[132:133]
	v_or_b32_e32 v40, 3, v65
	v_sub_u32_e32 v65, v43, v40
	v_cvt_f32_u32_e32 v133, v65
	s_or_b64 s[0:1], s[4:5], s[0:1]
	s_and_b64 vcc, vcc, s[0:1]
	v_cmp_lt_i32_e64 s[0:1], s18, v40
	v_mov_b32_e32 v40, v15
	v_sub_f32_e32 v14, v66, v67
	v_pk_mul_f32 v[66:67], v[40:41], v[132:133]
	v_cndmask_b32_e32 v14, v178, v14, vcc
	v_sub_f32_e32 v15, v66, v67
	v_or_b32_e32 v67, v64, v62
	v_sub_u32_e32 v40, v43, v67
	v_cvt_f32_u32_e32 v133, v40
	v_cmp_gt_u32_e32 vcc, s19, v65
	s_or_b64 s[0:1], s[4:5], s[0:1]
	s_and_b64 vcc, vcc, s[0:1]
	v_cndmask_b32_e32 v15, v178, v15, vcc
	v_cmp_gt_u32_e32 vcc, s19, v40
	v_mov_b32_e32 v40, v8
	v_pk_mul_f32 v[64:65], v[40:41], v[132:133]
	v_xad_u32 v40, v67, -1, v43
	v_cmp_lt_i32_e64 s[0:1], s18, v67
	v_cvt_f32_u32_e32 v133, v40
	s_or_b64 s[0:1], s[4:5], s[0:1]
	s_and_b64 vcc, vcc, s[0:1]
	v_sub_f32_e32 v8, v64, v65
	v_cndmask_b32_e32 v8, v178, v8, vcc
	v_cmp_gt_u32_e32 vcc, s19, v40
	v_mov_b32_e32 v40, v9
	v_pk_mul_f32 v[64:65], v[40:41], v[132:133]
	v_or_b32_e32 v40, 2, v67
	v_sub_f32_e32 v9, v64, v65
	v_sub_u32_e32 v64, v43, v40
	v_cvt_f32_u32_e32 v133, v64
	v_cmp_lt_i32_e64 s[0:1], s20, v67
	s_or_b64 s[0:1], s[4:5], s[0:1]
	s_and_b64 vcc, vcc, s[0:1]
	v_cmp_lt_i32_e64 s[0:1], s18, v40
	v_mov_b32_e32 v40, v10
	v_cndmask_b32_e32 v9, v178, v9, vcc
	v_cmp_gt_u32_e32 vcc, s19, v64
	v_pk_mul_f32 v[64:65], v[40:41], v[132:133]
	v_or_b32_e32 v40, 3, v67
	v_sub_f32_e32 v10, v64, v65
	v_sub_u32_e32 v64, v43, v40
	v_cvt_f32_u32_e32 v133, v64
	s_or_b64 s[0:1], s[4:5], s[0:1]
	s_and_b64 vcc, vcc, s[0:1]
	v_cmp_lt_i32_e64 s[0:1], s18, v40
	v_mov_b32_e32 v40, v11
	v_cndmask_b32_e32 v10, v178, v10, vcc
	v_cmp_gt_u32_e32 vcc, s19, v64
	v_pk_mul_f32 v[64:65], v[40:41], v[132:133]
	v_sub_u32_e32 v40, v43, v63
	v_cvt_f32_u32_e32 v133, v40
	s_or_b64 s[0:1], s[4:5], s[0:1]
	s_and_b64 vcc, vcc, s[0:1]
	v_sub_f32_e32 v11, v64, v65
	v_cndmask_b32_e32 v11, v178, v11, vcc
	v_cmp_gt_u32_e32 vcc, s19, v40
	v_mov_b32_e32 v40, v4
	v_pk_mul_f32 v[64:65], v[40:41], v[132:133]
	v_xad_u32 v40, v63, -1, v43
	v_cmp_lt_i32_e64 s[0:1], s18, v63
	v_cvt_f32_u32_e32 v133, v40
	s_or_b64 s[0:1], s[4:5], s[0:1]
	s_and_b64 vcc, vcc, s[0:1]
	v_sub_f32_e32 v4, v64, v65
	v_cndmask_b32_e32 v4, v178, v4, vcc
	v_cmp_gt_u32_e32 vcc, s19, v40
	v_mov_b32_e32 v40, v5
	v_pk_mul_f32 v[64:65], v[40:41], v[132:133]
	v_or_b32_e32 v40, 2, v63
	v_sub_f32_e32 v5, v64, v65
	v_sub_u32_e32 v64, v43, v40
	v_cvt_f32_u32_e32 v133, v64
	v_cmp_lt_i32_e64 s[0:1], s20, v63
	s_or_b64 s[0:1], s[4:5], s[0:1]
	s_and_b64 vcc, vcc, s[0:1]
	v_cmp_lt_i32_e64 s[0:1], s18, v40
	v_mov_b32_e32 v40, v6
	v_cndmask_b32_e32 v5, v178, v5, vcc
	v_cmp_gt_u32_e32 vcc, s19, v64
	v_pk_mul_f32 v[64:65], v[40:41], v[132:133]
	v_or_b32_e32 v40, 3, v63
	v_sub_u32_e32 v63, v43, v40
	v_cvt_f32_u32_e32 v133, v63
	s_or_b64 s[0:1], s[4:5], s[0:1]
	s_and_b64 vcc, vcc, s[0:1]
	v_cmp_lt_i32_e64 s[0:1], s18, v40
	v_mov_b32_e32 v40, v7
	v_sub_f32_e32 v6, v64, v65
	v_pk_mul_f32 v[64:65], v[40:41], v[132:133]
	v_sub_u32_e32 v40, v43, v61
	v_cvt_f32_u32_e32 v133, v40
	v_cndmask_b32_e32 v6, v178, v6, vcc
	v_cmp_gt_u32_e32 vcc, s19, v63
	s_or_b64 s[0:1], s[4:5], s[0:1]
	s_and_b64 vcc, vcc, s[0:1]
	v_sub_f32_e32 v7, v64, v65
; __device__ __forceinline__ void swa_prompt_unit(const Ctx& P, int li, int b, int qh, int n, LAS unsigned char* lds, const bf16_t* PROJ, bf16_t* H, int tid) {
;     ...
;     mx = fmaxf(mx, __shfl_xor(mx, 16)); mx = fmaxf(mx, __shfl_xor(mx, 32));
;     const float m = fmaxf(mx, sink);
;     float sum = 0.f;
; #pragma unroll
;     for (int cbi = 0; cbi < 10; ++cbi)
; #pragma unroll
;         for (int t = 0; t < 4; ++t) { const float p = __expf(sc[cbi][t] - m); sc[cbi][t] = p; sum += p; }
	v_cndmask_b32_e32 v7, v178, v7, vcc
	v_cmp_gt_u32_e32 vcc, s19, v40
	v_cmp_lt_i32_e64 s[0:1], s18, v61
	v_mov_b32_e32 v40, v0
	s_or_b64 s[0:1], s[4:5], s[0:1]
	v_pk_mul_f32 v[62:63], v[40:41], v[132:133]
	s_and_b64 vcc, vcc, s[0:1]
	v_sub_f32_e32 v0, v62, v63
	v_cndmask_b32_e32 v62, v178, v0, vcc
	v_xad_u32 v0, v61, -1, v43
	v_cvt_f32_u32_e32 v133, v0
	v_cmp_lt_i32_e64 s[0:1], s20, v61
	v_mov_b32_e32 v40, v1
	v_cmp_gt_u32_e32 vcc, s19, v0
	s_or_b64 s[0:1], s[4:5], s[0:1]
	v_pk_mul_f32 v[0:1], v[40:41], v[132:133]
	s_and_b64 vcc, vcc, s[0:1]
	v_sub_f32_e32 v0, v0, v1
	v_max3_f32 v72, v74, v38, v39
	v_cndmask_b32_e32 v63, v178, v0, vcc
	v_or_b32_e32 v0, 2, v61
	v_max3_f32 v72, v72, v32, v33
	v_sub_u32_e32 v1, v43, v0
	v_max3_f32 v72, v72, v34, v35
	v_cvt_f32_u32_e32 v133, v1
	v_max3_f32 v72, v72, v28, v29
	v_max3_f32 v70, v72, v30, v31
	v_max3_f32 v70, v70, v24, v25
	v_cmp_lt_i32_e64 s[0:1], s18, v0
	v_mov_b32_e32 v40, v2
	v_max3_f32 v70, v70, v26, v27
	v_cmp_gt_u32_e32 vcc, s19, v1
	s_or_b64 s[0:1], s[4:5], s[0:1]
	v_pk_mul_f32 v[0:1], v[40:41], v[132:133]
	v_max3_f32 v70, v70, v20, v21
	s_and_b64 vcc, vcc, s[0:1]
	v_sub_f32_e32 v0, v0, v1
	v_max3_f32 v68, v70, v22, v23
	v_cndmask_b32_e32 v2, v178, v0, vcc
	v_or_b32_e32 v0, 3, v61
	v_max3_f32 v68, v68, v16, v17
	v_sub_u32_e32 v1, v43, v0
	v_max3_f32 v68, v68, v18, v19
	v_cvt_f32_u32_e32 v133, v1
	v_max3_f32 v68, v68, v12, v13
	v_max3_f32 v66, v68, v14, v15
	v_max3_f32 v66, v66, v8, v9
	v_cmp_lt_i32_e64 s[0:1], s18, v0
	v_mov_b32_e32 v40, v3
	v_max3_f32 v66, v66, v10, v11
	v_cmp_gt_u32_e32 vcc, s19, v1
	s_or_b64 s[0:1], s[4:5], s[0:1]
	v_pk_mul_f32 v[0:1], v[40:41], v[132:133]
	v_and_b32_e32 v40, 64, v166
	v_max3_f32 v66, v66, v4, v5
	s_and_b64 vcc, vcc, s[0:1]
	v_sub_f32_e32 v0, v0, v1
	v_xor_b32_e32 v3, 16, v166
	v_add_u32_e32 v40, 64, v40
	v_max3_f32 v64, v66, v6, v7
	v_cndmask_b32_e32 v0, v178, v0, vcc
	v_cmp_lt_i32_e32 vcc, v3, v40
	v_max3_f32 v64, v64, v62, v63
	v_max3_f32 v1, v64, v2, v0
	v_cndmask_b32_e32 v3, v166, v3, vcc
	v_lshlrev_b32_e32 v3, 2, v3
	ds_bpermute_b32 v41, v3, v1
	s_waitcnt lgkmcnt(0)
	v_max_f32_e32 v41, v41, v41
	v_max_f32_e32 v1, v1, v41
	v_xor_b32_e32 v41, 32, v166
	v_cmp_lt_i32_e32 vcc, v41, v40
	s_nop 1
	v_cndmask_b32_e32 v40, v166, v41, vcc
	v_lshlrev_b32_e32 v40, 2, v40
	ds_bpermute_b32 v41, v40, v1
	s_waitcnt vmcnt(0) lgkmcnt(0)
	v_max3_f32 v1, v1, v41, v42
	v_sub_f32_e32 v36, v36, v1
	v_mul_f32_e32 v36, 0x3fb8aa3b, v36
	v_sub_f32_e32 v37, v37, v1
	v_exp_f32_e32 v36, v36
	v_mul_f32_e32 v37, 0x3fb8aa3b, v37
	v_sub_f32_e32 v38, v38, v1
	v_exp_f32_e32 v37, v37
	v_mul_f32_e32 v38, 0x3fb8aa3b, v38
	v_sub_f32_e32 v39, v39, v1
	v_exp_f32_e32 v38, v38
	v_mul_f32_e32 v39, 0x3fb8aa3b, v39
	v_sub_f32_e32 v32, v32, v1
	v_exp_f32_e32 v39, v39
	v_mul_f32_e32 v32, 0x3fb8aa3b, v32
	v_sub_f32_e32 v33, v33, v1
	v_add_f32_e32 v41, 0, v36
	v_exp_f32_e32 v32, v32
	v_mul_f32_e32 v33, 0x3fb8aa3b, v33
	v_sub_f32_e32 v34, v34, v1
	v_add_f32_e32 v41, v37, v41
	v_exp_f32_e32 v33, v33
	v_mul_f32_e32 v34, 0x3fb8aa3b, v34
	v_sub_f32_e32 v35, v35, v1
	v_add_f32_e32 v41, v38, v41
	v_exp_f32_e32 v34, v34
	v_mul_f32_e32 v35, 0x3fb8aa3b, v35
	v_sub_f32_e32 v28, v28, v1
	v_add_f32_e32 v41, v39, v41
	v_exp_f32_e32 v35, v35
	v_mul_f32_e32 v28, 0x3fb8aa3b, v28
	v_sub_f32_e32 v29, v29, v1
	v_add_f32_e32 v41, v32, v41
	v_exp_f32_e32 v28, v28
	v_mul_f32_e32 v29, 0x3fb8aa3b, v29
	v_sub_f32_e32 v30, v30, v1
	v_add_f32_e32 v41, v33, v41
	v_exp_f32_e32 v29, v29
	v_mul_f32_e32 v30, 0x3fb8aa3b, v30
	v_sub_f32_e32 v31, v31, v1
	v_add_f32_e32 v41, v34, v41
	v_exp_f32_e32 v30, v30
	v_mul_f32_e32 v31, 0x3fb8aa3b, v31
	v_sub_f32_e32 v24, v24, v1
	v_add_f32_e32 v41, v35, v41
	v_exp_f32_e32 v31, v31
	v_mul_f32_e32 v24, 0x3fb8aa3b, v24
	v_sub_f32_e32 v25, v25, v1
	v_add_f32_e32 v41, v28, v41
	v_exp_f32_e32 v24, v24
	v_mul_f32_e32 v25, 0x3fb8aa3b, v25
	v_sub_f32_e32 v26, v26, v1
	v_add_f32_e32 v41, v29, v41
	v_exp_f32_e32 v25, v25
	v_mul_f32_e32 v26, 0x3fb8aa3b, v26
	v_sub_f32_e32 v27, v27, v1
	v_add_f32_e32 v41, v30, v41
	v_exp_f32_e32 v26, v26
	v_mul_f32_e32 v27, 0x3fb8aa3b, v27
	v_sub_f32_e32 v20, v20, v1
	v_add_f32_e32 v41, v31, v41
	v_exp_f32_e32 v27, v27
	v_mul_f32_e32 v20, 0x3fb8aa3b, v20
	v_sub_f32_e32 v21, v21, v1
	v_add_f32_e32 v41, v24, v41
	v_exp_f32_e32 v20, v20
	v_mul_f32_e32 v21, 0x3fb8aa3b, v21
	v_sub_f32_e32 v22, v22, v1
	v_add_f32_e32 v41, v25, v41
	v_exp_f32_e32 v21, v21
	v_mul_f32_e32 v22, 0x3fb8aa3b, v22
	v_sub_f32_e32 v23, v23, v1
	v_add_f32_e32 v41, v26, v41
	v_exp_f32_e32 v22, v22
	v_mul_f32_e32 v23, 0x3fb8aa3b, v23
	v_sub_f32_e32 v16, v16, v1
	v_add_f32_e32 v41, v27, v41
	v_exp_f32_e32 v23, v23
	v_mul_f32_e32 v16, 0x3fb8aa3b, v16
	v_sub_f32_e32 v17, v17, v1
	v_add_f32_e32 v41, v20, v41
	v_exp_f32_e32 v16, v16
	v_mul_f32_e32 v17, 0x3fb8aa3b, v17
	v_sub_f32_e32 v18, v18, v1
	v_add_f32_e32 v41, v21, v41
	v_exp_f32_e32 v17, v17
	v_mul_f32_e32 v18, 0x3fb8aa3b, v18
	v_sub_f32_e32 v19, v19, v1
	v_add_f32_e32 v41, v22, v41
	v_exp_f32_e32 v18, v18
	v_mul_f32_e32 v19, 0x3fb8aa3b, v19
	v_sub_f32_e32 v12, v12, v1
	v_add_f32_e32 v41, v23, v41
	v_exp_f32_e32 v19, v19
	v_mul_f32_e32 v12, 0x3fb8aa3b, v12
	v_sub_f32_e32 v13, v13, v1
	v_add_f32_e32 v41, v16, v41
	v_exp_f32_e32 v12, v12
	v_mul_f32_e32 v13, 0x3fb8aa3b, v13
	v_sub_f32_e32 v14, v14, v1
	v_add_f32_e32 v41, v17, v41
	v_exp_f32_e32 v13, v13
	v_mul_f32_e32 v14, 0x3fb8aa3b, v14
	v_sub_f32_e32 v15, v15, v1
	v_add_f32_e32 v41, v18, v41
	v_exp_f32_e32 v14, v14
	v_mul_f32_e32 v15, 0x3fb8aa3b, v15
	v_sub_f32_e32 v8, v8, v1
	v_add_f32_e32 v41, v19, v41
	v_exp_f32_e32 v15, v15
	v_mul_f32_e32 v8, 0x3fb8aa3b, v8
	v_sub_f32_e32 v9, v9, v1
	v_add_f32_e32 v41, v12, v41
; #define LAS __attribute__((address_space(3)))
; __device__ __forceinline__ unsigned pk_bf16(float lo, float hi) { unsigned r; asm volatile("v_cvt_pk_bf16_f32 %0, %1, %2" : "=v"(r) : "v"(lo), "v"(hi)); return r; }
; __device__ __forceinline__ void lds_wave_sync() { asm volatile("s_waitcnt lgkmcnt(0)" ::: "memory"); }
; __device__ __forceinline__ void swa_prompt_unit(const Ctx& P, int li, int b, int qh, int n, LAS unsigned char* lds, const bf16_t* PROJ, bf16_t* H, int tid) {
;     ...
;     float sum = 0.f;
; #pragma unroll
;     for (int cbi = 0; cbi < 10; ++cbi)
; #pragma unroll
;         for (int t = 0; t < 4; ++t) { const float p = __expf(sc[cbi][t] - m); sc[cbi][t] = p; sum += p; }
;     sum += __shfl_xor(sum, 16); sum += __shfl_xor(sum, 32);
;     const float inv = 1.0f / (sum + __expf(sink - m));
; #pragma unroll
;     for (int cbi = 0; cbi < 10; ++cbi) { u32x2 w; w.x = pk_bf16(sc[cbi][0] * inv, sc[cbi][1] * inv); w.y = pk_bf16(sc[cbi][2] * inv, sc[cbi][3] * inv);
;         *(LAS u32x2*)(Pm + i * 528 + (16 * (cb0 + cbi) + 4 * fq) * 2) = w; }
;     lds_wave_sync();
	v_exp_f32_e32 v8, v8
	v_mul_f32_e32 v9, 0x3fb8aa3b, v9
	v_sub_f32_e32 v10, v10, v1
	v_add_f32_e32 v41, v13, v41
	v_exp_f32_e32 v9, v9
	v_mul_f32_e32 v10, 0x3fb8aa3b, v10
	v_sub_f32_e32 v11, v11, v1
	v_add_f32_e32 v41, v14, v41
	v_exp_f32_e32 v10, v10
	v_mul_f32_e32 v11, 0x3fb8aa3b, v11
	v_sub_f32_e32 v4, v4, v1
	v_add_f32_e32 v41, v15, v41
	v_exp_f32_e32 v11, v11
	v_mul_f32_e32 v4, 0x3fb8aa3b, v4
	v_sub_f32_e32 v5, v5, v1
	v_add_f32_e32 v41, v8, v41
	v_exp_f32_e32 v4, v4
	v_mul_f32_e32 v5, 0x3fb8aa3b, v5
	v_sub_f32_e32 v6, v6, v1
	v_add_f32_e32 v41, v9, v41
	v_exp_f32_e32 v5, v5
	v_mul_f32_e32 v6, 0x3fb8aa3b, v6
	v_sub_f32_e32 v7, v7, v1
	v_add_f32_e32 v41, v10, v41
	v_exp_f32_e32 v6, v6
	v_mul_f32_e32 v7, 0x3fb8aa3b, v7
	v_sub_f32_e32 v43, v62, v1
	v_add_f32_e32 v41, v11, v41
	v_exp_f32_e32 v7, v7
	v_mul_f32_e32 v43, 0x3fb8aa3b, v43
	v_sub_f32_e32 v61, v63, v1
	v_add_f32_e32 v41, v4, v41
	v_exp_f32_e32 v43, v43
	v_mul_f32_e32 v61, 0x3fb8aa3b, v61
	v_sub_f32_e32 v2, v2, v1
	v_add_f32_e32 v41, v5, v41
	v_exp_f32_e32 v61, v61
	v_mul_f32_e32 v2, 0x3fb8aa3b, v2
	v_sub_f32_e32 v0, v0, v1
	v_add_f32_e32 v41, v6, v41
	v_exp_f32_e32 v2, v2
	v_mul_f32_e32 v0, 0x3fb8aa3b, v0
	v_add_f32_e32 v41, v7, v41
	v_exp_f32_e32 v62, v0
	v_add_f32_e32 v41, v43, v41
	v_add_f32_e32 v41, v61, v41
	v_add_f32_e32 v41, v2, v41
	v_add_f32_e32 v0, v62, v41
	ds_bpermute_b32 v3, v3, v0
	v_sub_f32_e32 v1, v42, v1
	v_mul_f32_e32 v1, 0x3fb8aa3b, v1
	v_exp_f32_e32 v1, v1
	s_waitcnt lgkmcnt(0)
	v_add_f32_e32 v0, v0, v3
	ds_bpermute_b32 v3, v40, v0
	s_waitcnt lgkmcnt(0)
	v_add_f32_e32 v0, v0, v3
	v_add_f32_e32 v0, v1, v0
	v_div_scale_f32 v1, s[0:1], v0, v0, 1.0
	v_rcp_f32_e32 v3, v1
	s_movk_i32 s0, 0x210
	v_fma_f32 v40, -v1, v3, 1.0
	v_fmac_f32_e32 v3, v40, v3
	v_div_scale_f32 v40, vcc, 1.0, v0, 1.0
	v_mul_f32_e32 v41, v40, v3
	v_fma_f32 v42, -v1, v41, v40
	v_fmac_f32_e32 v41, v42, v3
	v_fma_f32 v1, -v1, v41, v40
	v_div_fmas_f32 v1, v1, v3, v41
	v_div_fixup_f32 v3, v1, v0, 1.0
	v_mul_lo_u32 v0, v50, s0
	v_readlane_b32 s0, v252, 7
	v_mul_f32_e32 v1, v37, v3
	s_nop 0
	v_add_u32_e32 v40, s0, v0
	v_mul_f32_e32 v0, v36, v3
	v_cvt_pk_bf16_f32 v0, v0, v1
	v_mul_f32_e32 v1, v38, v3
	v_mul_f32_e32 v36, v39, v3
	v_add_u32_e32 v41, v40, v128
	v_cvt_pk_bf16_f32 v1, v1, v36
	v_lshlrev_b32_e32 v36, 6, v49
	v_add_u32_e32 v37, v41, v36
	ds_write_b64 v37, v[0:1]
	v_mul_f32_e32 v0, v32, v3
	v_mul_f32_e32 v1, v33, v3
	v_cvt_pk_bf16_f32 v0, v0, v1
	v_mul_f32_e32 v1, v34, v3
	v_mul_f32_e32 v32, v35, v3
	v_cvt_pk_bf16_f32 v1, v1, v32
	v_lshl_add_u32 v32, v51, 5, v41
	ds_write_b64 v32, v[0:1]
	v_mul_f32_e32 v0, v28, v3
	v_mul_f32_e32 v1, v29, v3
	v_cvt_pk_bf16_f32 v0, v0, v1
	v_mul_f32_e32 v1, v30, v3
	v_mul_f32_e32 v28, v31, v3
	v_cvt_pk_bf16_f32 v1, v1, v28
	v_lshl_add_u32 v28, v53, 5, v41
	ds_write_b64 v28, v[0:1]
	v_mul_f32_e32 v0, v24, v3
	v_mul_f32_e32 v1, v25, v3
	v_cvt_pk_bf16_f32 v0, v0, v1
	v_mul_f32_e32 v1, v26, v3
	v_mul_f32_e32 v24, v27, v3
	v_cvt_pk_bf16_f32 v1, v1, v24
	v_lshl_add_u32 v24, v54, 5, v41
	ds_write_b64 v24, v[0:1]
	v_mul_f32_e32 v0, v20, v3
	v_mul_f32_e32 v1, v21, v3
	v_cvt_pk_bf16_f32 v0, v0, v1
	v_mul_f32_e32 v1, v22, v3
	v_mul_f32_e32 v20, v23, v3
	v_cvt_pk_bf16_f32 v1, v1, v20
	v_lshl_add_u32 v20, v55, 5, v41
	ds_write_b64 v20, v[0:1]
	v_mul_f32_e32 v0, v16, v3
	v_mul_f32_e32 v1, v17, v3
	v_cvt_pk_bf16_f32 v0, v0, v1
	v_mul_f32_e32 v1, v18, v3
	v_mul_f32_e32 v16, v19, v3
	v_cvt_pk_bf16_f32 v1, v1, v16
	v_lshl_add_u32 v16, v56, 5, v41
	ds_write_b64 v16, v[0:1]
	v_mul_f32_e32 v0, v12, v3
	v_mul_f32_e32 v1, v13, v3
	v_cvt_pk_bf16_f32 v0, v0, v1
	v_mul_f32_e32 v1, v14, v3
	v_mul_f32_e32 v12, v15, v3
	v_cvt_pk_bf16_f32 v1, v1, v12
	v_lshl_add_u32 v12, v57, 5, v41
	ds_write_b64 v12, v[0:1]
	v_mul_f32_e32 v0, v8, v3
	v_mul_f32_e32 v1, v9, v3
	v_cvt_pk_bf16_f32 v0, v0, v1
	v_mul_f32_e32 v1, v10, v3
	v_mul_f32_e32 v8, v11, v3
	v_cvt_pk_bf16_f32 v1, v1, v8
	v_lshl_add_u32 v8, v58, 5, v41
	ds_write_b64 v8, v[0:1]
	v_mul_f32_e32 v0, v4, v3
	v_mul_f32_e32 v1, v5, v3
	v_cvt_pk_bf16_f32 v0, v0, v1
	v_mul_f32_e32 v1, v6, v3
	v_mul_f32_e32 v4, v7, v3
	v_cvt_pk_bf16_f32 v1, v1, v4
	v_lshl_add_u32 v4, v59, 5, v41
	ds_write_b64 v4, v[0:1]
	v_mul_f32_e32 v0, v43, v3
	v_mul_f32_e32 v1, v61, v3
	v_cvt_pk_bf16_f32 v0, v0, v1
	v_mul_f32_e32 v1, v2, v3
	v_mul_f32_e32 v2, v62, v3
	v_cvt_pk_bf16_f32 v1, v1, v2
	v_lshl_add_u32 v2, v60, 5, v41
	ds_write_b64 v2, v[0:1]
	v_mul_u32_u24_e32 v20, 0x210, v52
	v_or_b32_e32 v4, v48, v36
	s_waitcnt lgkmcnt(0)
; #define LAS __attribute__((address_space(3)))
; __device__ __forceinline__ unsigned pk_bf16(float lo, float hi) { unsigned r; asm volatile("v_cvt_pk_bf16_f32 %0, %1, %2" : "=v"(r) : "v"(lo), "v"(hi)); return r; }
; __device__ __forceinline__ f32x4 mfma16(bf16x8 a, bf16x8 b, f32x4 c) { return __builtin_amdgcn_mfma_f32_16x16x32_bf16(a, b, c, 0, 0, 0); }
; __device__ __forceinline__ void swa_prompt_unit(const Ctx& P, int li, int b, int qh, int n, LAS unsigned char* lds, const bf16_t* PROJ, bf16_t* H, int tid) {
;     ...
;     f32x4 o[4];
; #pragma unroll
;     for (int eb = 0; eb < 4; ++eb) o[eb] = (f32x4){0.f, 0.f, 0.f, 0.f};
;     const int kk0 = wave >> 1;
; #pragma unroll
;     for (int kki = 0; kki < 5; ++kki) { const int kk = kk0 + kki; const bf16x8 pf = *(const LAS bf16x8*)(Pm + i * 528 + (32 * kk + 8 * fq) * 2);
; #pragma unroll
;         for (int eb = 0; eb < 4; ++eb) { const bf16x8 vf = *(const LAS bf16x8*)(VT + (16 * eb + fr) * 528 + (32 * kk + 8 * fq) * 2); o[eb] = mfma16(vf, pf, o[eb]); } }
; #pragma unroll
;     for (int eb = 0; eb < 4; ++eb) { u32x2 w; w.x = pk_bf16(o[eb][0], o[eb][1]); w.y = pk_bf16(o[eb][2], o[eb][3]);
;         *(u32x2*)(H + qrow * DM + 1024 + qh * 64 + 16 * eb + 4 * fq) = w; }
;     __syncthreads();
	v_add_u32_e32 v24, v40, v4
	v_add3_u32 v16, 0, v4, v20
	ds_read_b128 v[0:3], v24
	ds_read_b128 v[12:15], v16 offset:53760
	ds_read_b128 v[4:7], v16 offset:36864
	ds_read_b128 v[8:11], v16 offset:45312
	ds_read_b128 v[16:19], v16 offset:62208
	v_add3_u32 v25, v46, v36, v20
	ds_read_b128 v[20:23], v25 offset:36928
	s_waitcnt lgkmcnt(3)
	v_mfma_f32_16x16x32_bf16 v[4:7], v[4:7], v[0:3], 0
	s_waitcnt lgkmcnt(2)
	v_mfma_f32_16x16x32_bf16 v[8:11], v[8:11], v[0:3], 0
	v_mfma_f32_16x16x32_bf16 v[12:15], v[12:15], v[0:3], 0
	s_waitcnt lgkmcnt(1)
	v_mfma_f32_16x16x32_bf16 v[0:3], v[16:19], v[0:3], 0
	ds_read_b128 v[16:19], v24 offset:64
	s_waitcnt lgkmcnt(0)
	v_mfma_f32_16x16x32_bf16 v[4:7], v[20:23], v[16:19], v[4:7]
	ds_read_b128 v[20:23], v25 offset:45376
	s_waitcnt lgkmcnt(0)
	v_mfma_f32_16x16x32_bf16 v[8:11], v[20:23], v[16:19], v[8:11]
	ds_read_b128 v[20:23], v25 offset:53824
	s_waitcnt lgkmcnt(0)
	v_mfma_f32_16x16x32_bf16 v[12:15], v[20:23], v[16:19], v[12:15]
	ds_read_b128 v[20:23], v25 offset:62272
	s_waitcnt lgkmcnt(0)
	v_mfma_f32_16x16x32_bf16 v[0:3], v[20:23], v[16:19], v[0:3]
	ds_read_b128 v[16:19], v24 offset:128
	ds_read_b128 v[20:23], v25 offset:36992
	s_waitcnt lgkmcnt(0)
	v_mfma_f32_16x16x32_bf16 v[4:7], v[20:23], v[16:19], v[4:7]
	ds_read_b128 v[20:23], v25 offset:45440
	s_waitcnt lgkmcnt(0)
	v_mfma_f32_16x16x32_bf16 v[8:11], v[20:23], v[16:19], v[8:11]
	ds_read_b128 v[20:23], v25 offset:53888
	s_waitcnt lgkmcnt(0)
	v_mfma_f32_16x16x32_bf16 v[12:15], v[20:23], v[16:19], v[12:15]
	ds_read_b128 v[20:23], v25 offset:62336
	s_waitcnt lgkmcnt(0)
	v_mfma_f32_16x16x32_bf16 v[0:3], v[20:23], v[16:19], v[0:3]
	ds_read_b128 v[16:19], v24 offset:192
	ds_read_b128 v[20:23], v25 offset:37056
	s_waitcnt lgkmcnt(0)
	v_mfma_f32_16x16x32_bf16 v[4:7], v[20:23], v[16:19], v[4:7]
	ds_read_b128 v[20:23], v25 offset:45504
	s_waitcnt lgkmcnt(0)
	v_mfma_f32_16x16x32_bf16 v[8:11], v[20:23], v[16:19], v[8:11]
	ds_read_b128 v[20:23], v25 offset:53952
	s_waitcnt lgkmcnt(0)
	v_mfma_f32_16x16x32_bf16 v[12:15], v[20:23], v[16:19], v[12:15]
	ds_read_b128 v[20:23], v25 offset:62400
	s_waitcnt lgkmcnt(0)
	v_mfma_f32_16x16x32_bf16 v[0:3], v[20:23], v[16:19], v[0:3]
	ds_read_b128 v[16:19], v24 offset:256
	ds_read_b128 v[20:23], v25 offset:37120
	s_waitcnt lgkmcnt(0)
	v_mfma_f32_16x16x32_bf16 v[4:7], v[20:23], v[16:19], v[4:7]
	ds_read_b128 v[20:23], v25 offset:45568
	s_waitcnt lgkmcnt(0)
	v_mfma_f32_16x16x32_bf16 v[8:11], v[20:23], v[16:19], v[8:11]
	ds_read_b128 v[20:23], v25 offset:54016
	s_waitcnt lgkmcnt(0)
	v_mfma_f32_16x16x32_bf16 v[12:15], v[20:23], v[16:19], v[12:15]
	ds_read_b128 v[20:23], v25 offset:62464
	v_cvt_pk_bf16_f32 v4, v4, v5
	v_cvt_pk_bf16_f32 v5, v6, v7
	s_waitcnt lgkmcnt(0)
	v_mfma_f32_16x16x32_bf16 v[0:3], v[20:23], v[16:19], v[0:3]
	v_lshlrev_b64 v[16:17], 12, v[44:45]
	v_lshl_add_u64 v[16:17], s[6:7], 0, v[16:17]
	v_lshl_add_u64 v[16:17], v[16:17], 0, s[24:25]
	v_lshl_add_u64 v[16:17], v[16:17], 0, v[128:129]
	global_store_dwordx2 v[16:17], v[4:5], off offset:2048
	v_cvt_pk_bf16_f32 v4, v8, v9
	v_cvt_pk_bf16_f32 v5, v10, v11
	global_store_dwordx2 v[16:17], v[4:5], off offset:2080
	v_cvt_pk_bf16_f32 v4, v12, v13
	v_cvt_pk_bf16_f32 v5, v14, v15
	global_store_dwordx2 v[16:17], v[4:5], off offset:2112
	v_cvt_pk_bf16_f32 v0, v0, v1
	v_cvt_pk_bf16_f32 v1, v2, v3
	s_nop 0
	global_store_dwordx2 v[16:17], v[0:1], off offset:2144
	s_barrier
	s_and_b32 s0, s38, 0xfffffe00
	s_cmpk_lg_i32 s0, 0x400
	v_and_b32_e32 v16, 0x7f, v47
	s_cbranch_scc0 .LBB0_470
